# ffn_fixup pre-phase of both FFN down projections: 6 channel-block iterations unrolled, all loads in flight before one wait
# baseline (speedup 1.0000x reference)
; __device__ __forceinline__ void ffn_fixup(int pm, const float* __restrict__ UH, const float* __restrict__ UT, const float* __restrict__ cw, const float* __restrict__ cb, bf16_t* __restrict__ ACT, int tid) {
;     ...
;     for (int f = tid; f < FF; f += 512) {
;         float cva[2], cvg[2];
; #pragma unroll
;         for (int hg = 0; hg < 2; ++hg) {
;             const int ch = hg * FF + f;
;             const float h0 = UH[(size_t)(pm * 2 + 0) * FF2 + ch], h1 = UH[(size_t)(pm * 2 + 1) * FF2 + ch];
;             const float q2 = UT[(size_t)((pm - 1) * 2 + 0) * FF2 + ch], q1 = UT[(size_t)((pm - 1) * 2 + 1) * FF2 + ch];
;             const float w0 = cw[ch], w1 = cw[FF2 + ch], w2 = cw[2 * FF2 + ch], bb = cb[ch];
.LBB0_703:
	v_lshl_add_u64 v[14:15], s[14:15], 0, v[2:3]
	v_add_co_u32_e32 v22, vcc, 0x1e200000, v14
	v_lshl_add_u64 v[16:17], s[16:17], 0, v[2:3]
	s_nop 0
	v_addc_co_u32_e32 v23, vcc, 0, v15, vcc
	v_add_co_u32_e32 v24, vcc, 0x1e205000, v14
	v_lshl_add_u64 v[18:19], s[22:23], 0, v[2:3]
	s_nop 0
	v_addc_co_u32_e32 v25, vcc, 0, v15, vcc
	v_add_co_u32_e32 v26, vcc, 0x1ea00000, v16
	v_lshl_add_u64 v[20:21], s[20:21], 0, v[2:3]
	s_nop 0
	v_addc_co_u32_e32 v27, vcc, 0, v17, vcc
	global_load_dword v40, v[18:19], off
	global_load_dword v41, v[20:21], off
	global_load_dword v42, v[22:23], off
	global_load_dword v43, v[24:25], off offset:2048
	v_add_co_u32_e32 v22, vcc, 0x1ea05000, v16
	v_ashrrev_i32_e32 v8, 6, v12
	s_nop 0
	v_addc_co_u32_e32 v23, vcc, 0, v17, vcc
	v_add_co_u32_e32 v24, vcc, 0x5000, v18
	global_load_dword v44, v[26:27], off
	global_load_dword v45, v[22:23], off offset:2048
	v_addc_co_u32_e32 v25, vcc, 0, v19, vcc
	v_add_co_u32_e32 v22, vcc, s25, v18
	s_add_u32 s14, s14, 0x800
	s_nop 0
	v_addc_co_u32_e32 v23, vcc, 0, v19, vcc
	v_add_co_u32_e32 v26, vcc, s26, v14
	global_load_dword v46, v[24:25], off offset:2048
	s_nop 0
	global_load_dword v47, v[22:23], off
	v_addc_co_u32_e32 v27, vcc, 0, v15, vcc
	v_add_co_u32_e32 v14, vcc, s27, v14
	s_addc_u32 s15, s15, 0
	s_nop 0
	v_addc_co_u32_e32 v15, vcc, 0, v15, vcc
	v_add_co_u32_e32 v22, vcc, s28, v16
	global_load_dword v48, v[26:27], off offset:3072
	s_nop 0
	global_load_dword v49, v[14:15], off offset:1024
	v_addc_co_u32_e32 v23, vcc, 0, v17, vcc
	v_add_co_u32_e32 v14, vcc, s29, v16
	global_load_dword v50, v[22:23], off offset:3072
	s_nop 0
	v_addc_co_u32_e32 v15, vcc, 0, v17, vcc
	v_add_co_u32_e32 v16, vcc, s30, v18
	s_add_u32 s16, s16, 0x800
	s_nop 0
	v_addc_co_u32_e32 v17, vcc, 0, v19, vcc
	v_add_co_u32_e32 v22, vcc, s31, v18
	global_load_dword v51, v[16:17], off offset:3072
	s_nop 0
	v_addc_co_u32_e32 v23, vcc, 0, v19, vcc
	v_add_co_u32_e32 v16, vcc, s34, v18
	s_addc_u32 s17, s17, 0
	s_nop 0
	v_addc_co_u32_e32 v17, vcc, 0, v19, vcc
	v_add_co_u32_e32 v18, vcc, s30, v20
	global_load_dword v52, v[22:23], off offset:1024
	s_nop 0
	global_load_dword v53, v[16:17], off offset:3072
	v_addc_co_u32_e32 v19, vcc, 0, v21, vcc
	global_load_dword v54, v[18:19], off offset:3072
	s_nop 0
	global_load_dword v55, v[14:15], off offset:1024
	v_and_or_b32 v15, v1, s35, v10
	v_add_u32_e32 v14, s41, v8
	v_lshlrev_b32_e32 v8, 1, v15
	v_ashrrev_i32_e32 v15, 31, v14
	v_lshlrev_b64 v[14:15], 15, v[14:15]
	v_lshl_add_u64 v[14:15], s[12:13], 0, v[14:15]
	v_lshl_add_u64 v[14:15], v[14:15], 0, v[8:9]
	v_add_u32_e32 v19, 0x200, v12
	v_mov_b32_e32 v12, v19
	s_add_u32 s22, s22, 0x800
	s_addc_u32 s23, s23, 0
	s_add_u32 s20, s20, 0x800
	s_addc_u32 s21, s21, 0
	v_add_u32_e32 v1, 0x2000, v1
	v_mov_b32_e32 v56, v14
	v_mov_b32_e32 v57, v15
	v_lshl_add_u64 v[14:15], s[14:15], 0, v[2:3]
	v_add_co_u32_e32 v22, vcc, 0x1e200000, v14
	v_lshl_add_u64 v[16:17], s[16:17], 0, v[2:3]
	s_nop 0
	v_addc_co_u32_e32 v23, vcc, 0, v15, vcc
	v_add_co_u32_e32 v24, vcc, 0x1e205000, v14
	v_lshl_add_u64 v[18:19], s[22:23], 0, v[2:3]
	s_nop 0
	v_addc_co_u32_e32 v25, vcc, 0, v15, vcc
	v_add_co_u32_e32 v26, vcc, 0x1ea00000, v16
	v_lshl_add_u64 v[20:21], s[20:21], 0, v[2:3]
	s_nop 0
	v_addc_co_u32_e32 v27, vcc, 0, v17, vcc
	global_load_dword v60, v[18:19], off
	global_load_dword v61, v[20:21], off
	global_load_dword v62, v[22:23], off
	global_load_dword v63, v[24:25], off offset:2048
	v_add_co_u32_e32 v22, vcc, 0x1ea05000, v16
	v_ashrrev_i32_e32 v8, 6, v12
	s_nop 0
	v_addc_co_u32_e32 v23, vcc, 0, v17, vcc
	v_add_co_u32_e32 v24, vcc, 0x5000, v18
	global_load_dword v64, v[26:27], off
	global_load_dword v65, v[22:23], off offset:2048
	v_addc_co_u32_e32 v25, vcc, 0, v19, vcc
	v_add_co_u32_e32 v22, vcc, s25, v18
	s_add_u32 s14, s14, 0x800
	s_nop 0
	v_addc_co_u32_e32 v23, vcc, 0, v19, vcc
	v_add_co_u32_e32 v26, vcc, s26, v14
	global_load_dword v66, v[24:25], off offset:2048
	s_nop 0
	global_load_dword v67, v[22:23], off
	v_addc_co_u32_e32 v27, vcc, 0, v15, vcc
	v_add_co_u32_e32 v14, vcc, s27, v14
	s_addc_u32 s15, s15, 0
	s_nop 0
	v_addc_co_u32_e32 v15, vcc, 0, v15, vcc
	v_add_co_u32_e32 v22, vcc, s28, v16
	global_load_dword v68, v[26:27], off offset:3072
	s_nop 0
	global_load_dword v69, v[14:15], off offset:1024
	v_addc_co_u32_e32 v23, vcc, 0, v17, vcc
	v_add_co_u32_e32 v14, vcc, s29, v16
	global_load_dword v70, v[22:23], off offset:3072
	s_nop 0
	v_addc_co_u32_e32 v15, vcc, 0, v17, vcc
	v_add_co_u32_e32 v16, vcc, s30, v18
	s_add_u32 s16, s16, 0x800
	s_nop 0
	v_addc_co_u32_e32 v17, vcc, 0, v19, vcc
	v_add_co_u32_e32 v22, vcc, s31, v18
	global_load_dword v71, v[16:17], off offset:3072
	s_nop 0
	v_addc_co_u32_e32 v23, vcc, 0, v19, vcc
	v_add_co_u32_e32 v16, vcc, s34, v18
	s_addc_u32 s17, s17, 0
	s_nop 0
	v_addc_co_u32_e32 v17, vcc, 0, v19, vcc
	v_add_co_u32_e32 v18, vcc, s30, v20
	global_load_dword v72, v[22:23], off offset:1024
	s_nop 0
	global_load_dword v73, v[16:17], off offset:3072
	v_addc_co_u32_e32 v19, vcc, 0, v21, vcc
	global_load_dword v74, v[18:19], off offset:3072
	s_nop 0
	global_load_dword v75, v[14:15], off offset:1024
	v_and_or_b32 v15, v1, s35, v10
	v_add_u32_e32 v14, s41, v8
	v_lshlrev_b32_e32 v8, 1, v15
	v_ashrrev_i32_e32 v15, 31, v14
	v_lshlrev_b64 v[14:15], 15, v[14:15]
	v_lshl_add_u64 v[14:15], s[12:13], 0, v[14:15]
	v_lshl_add_u64 v[14:15], v[14:15], 0, v[8:9]
	v_add_u32_e32 v19, 0x200, v12
	v_mov_b32_e32 v12, v19
	s_add_u32 s22, s22, 0x800
	s_addc_u32 s23, s23, 0
	s_add_u32 s20, s20, 0x800
	s_addc_u32 s21, s21, 0
	v_add_u32_e32 v1, 0x2000, v1
	v_mov_b32_e32 v76, v14
	v_mov_b32_e32 v77, v15
	v_lshl_add_u64 v[14:15], s[14:15], 0, v[2:3]
; __device__ __forceinline__ void ffn_fixup(int pm, const float* __restrict__ UH, const float* __restrict__ UT, const float* __restrict__ cw, const float* __restrict__ cb, bf16_t* __restrict__ ACT, int tid) {
;     ...
;     for (int f = tid; f < FF; f += 512) {
;         float cva[2], cvg[2];
; #pragma unroll
;         for (int hg = 0; hg < 2; ++hg) {
;             const int ch = hg * FF + f;
;             const float h0 = UH[(size_t)(pm * 2 + 0) * FF2 + ch], h1 = UH[(size_t)(pm * 2 + 1) * FF2 + ch];
;             const float q2 = UT[(size_t)((pm - 1) * 2 + 0) * FF2 + ch], q1 = UT[(size_t)((pm - 1) * 2 + 1) * FF2 + ch];
;             const float w0 = cw[ch], w1 = cw[FF2 + ch], w2 = cw[2 * FF2 + ch], bb = cb[ch];
	v_add_co_u32_e32 v22, vcc, 0x1e200000, v14
	v_lshl_add_u64 v[16:17], s[16:17], 0, v[2:3]
	s_nop 0
	v_addc_co_u32_e32 v23, vcc, 0, v15, vcc
	v_add_co_u32_e32 v24, vcc, 0x1e205000, v14
	v_lshl_add_u64 v[18:19], s[22:23], 0, v[2:3]
	s_nop 0
	v_addc_co_u32_e32 v25, vcc, 0, v15, vcc
	v_add_co_u32_e32 v26, vcc, 0x1ea00000, v16
	v_lshl_add_u64 v[20:21], s[20:21], 0, v[2:3]
	s_nop 0
	v_addc_co_u32_e32 v27, vcc, 0, v17, vcc
	global_load_dword v80, v[18:19], off
	global_load_dword v81, v[20:21], off
	global_load_dword v82, v[22:23], off
	global_load_dword v83, v[24:25], off offset:2048
	v_add_co_u32_e32 v22, vcc, 0x1ea05000, v16
	v_ashrrev_i32_e32 v8, 6, v12
	s_nop 0
	v_addc_co_u32_e32 v23, vcc, 0, v17, vcc
	v_add_co_u32_e32 v24, vcc, 0x5000, v18
	global_load_dword v84, v[26:27], off
	global_load_dword v85, v[22:23], off offset:2048
	v_addc_co_u32_e32 v25, vcc, 0, v19, vcc
	v_add_co_u32_e32 v22, vcc, s25, v18
	s_add_u32 s14, s14, 0x800
	s_nop 0
	v_addc_co_u32_e32 v23, vcc, 0, v19, vcc
	v_add_co_u32_e32 v26, vcc, s26, v14
	global_load_dword v86, v[24:25], off offset:2048
	s_nop 0
	global_load_dword v87, v[22:23], off
	v_addc_co_u32_e32 v27, vcc, 0, v15, vcc
	v_add_co_u32_e32 v14, vcc, s27, v14
	s_addc_u32 s15, s15, 0
	s_nop 0
	v_addc_co_u32_e32 v15, vcc, 0, v15, vcc
	v_add_co_u32_e32 v22, vcc, s28, v16
	global_load_dword v88, v[26:27], off offset:3072
	s_nop 0
	global_load_dword v89, v[14:15], off offset:1024
	v_addc_co_u32_e32 v23, vcc, 0, v17, vcc
	v_add_co_u32_e32 v14, vcc, s29, v16
	global_load_dword v90, v[22:23], off offset:3072
	s_nop 0
	v_addc_co_u32_e32 v15, vcc, 0, v17, vcc
	v_add_co_u32_e32 v16, vcc, s30, v18
	s_add_u32 s16, s16, 0x800
	s_nop 0
	v_addc_co_u32_e32 v17, vcc, 0, v19, vcc
	v_add_co_u32_e32 v22, vcc, s31, v18
	global_load_dword v91, v[16:17], off offset:3072
	s_nop 0
	v_addc_co_u32_e32 v23, vcc, 0, v19, vcc
	v_add_co_u32_e32 v16, vcc, s34, v18
	s_addc_u32 s17, s17, 0
	s_nop 0
	v_addc_co_u32_e32 v17, vcc, 0, v19, vcc
	v_add_co_u32_e32 v18, vcc, s30, v20
	global_load_dword v92, v[22:23], off offset:1024
	s_nop 0
	global_load_dword v93, v[16:17], off offset:3072
	v_addc_co_u32_e32 v19, vcc, 0, v21, vcc
	global_load_dword v94, v[18:19], off offset:3072
	s_nop 0
	global_load_dword v95, v[14:15], off offset:1024
	v_and_or_b32 v15, v1, s35, v10
	v_add_u32_e32 v14, s41, v8
	v_lshlrev_b32_e32 v8, 1, v15
	v_ashrrev_i32_e32 v15, 31, v14
	v_lshlrev_b64 v[14:15], 15, v[14:15]
	v_lshl_add_u64 v[14:15], s[12:13], 0, v[14:15]
	v_lshl_add_u64 v[14:15], v[14:15], 0, v[8:9]
	v_add_u32_e32 v19, 0x200, v12
	v_mov_b32_e32 v12, v19
	s_add_u32 s22, s22, 0x800
	s_addc_u32 s23, s23, 0
	s_add_u32 s20, s20, 0x800
	s_addc_u32 s21, s21, 0
	v_add_u32_e32 v1, 0x2000, v1
	v_mov_b32_e32 v96, v14
	v_mov_b32_e32 v97, v15
	v_lshl_add_u64 v[14:15], s[14:15], 0, v[2:3]
	v_add_co_u32_e32 v22, vcc, 0x1e200000, v14
	v_lshl_add_u64 v[16:17], s[16:17], 0, v[2:3]
	s_nop 0
	v_addc_co_u32_e32 v23, vcc, 0, v15, vcc
	v_add_co_u32_e32 v24, vcc, 0x1e205000, v14
	v_lshl_add_u64 v[18:19], s[22:23], 0, v[2:3]
	s_nop 0
	v_addc_co_u32_e32 v25, vcc, 0, v15, vcc
	v_add_co_u32_e32 v26, vcc, 0x1ea00000, v16
	v_lshl_add_u64 v[20:21], s[20:21], 0, v[2:3]
	s_nop 0
	v_addc_co_u32_e32 v27, vcc, 0, v17, vcc
	global_load_dword v100, v[18:19], off
	global_load_dword v101, v[20:21], off
	global_load_dword v102, v[22:23], off
	global_load_dword v103, v[24:25], off offset:2048
	v_add_co_u32_e32 v22, vcc, 0x1ea05000, v16
	v_ashrrev_i32_e32 v8, 6, v12
	s_nop 0
	v_addc_co_u32_e32 v23, vcc, 0, v17, vcc
	v_add_co_u32_e32 v24, vcc, 0x5000, v18
	global_load_dword v104, v[26:27], off
	global_load_dword v105, v[22:23], off offset:2048
	v_addc_co_u32_e32 v25, vcc, 0, v19, vcc
	v_add_co_u32_e32 v22, vcc, s25, v18
	s_add_u32 s14, s14, 0x800
	s_nop 0
	v_addc_co_u32_e32 v23, vcc, 0, v19, vcc
	v_add_co_u32_e32 v26, vcc, s26, v14
	global_load_dword v106, v[24:25], off offset:2048
	s_nop 0
	global_load_dword v107, v[22:23], off
	v_addc_co_u32_e32 v27, vcc, 0, v15, vcc
	v_add_co_u32_e32 v14, vcc, s27, v14
	s_addc_u32 s15, s15, 0
	s_nop 0
	v_addc_co_u32_e32 v15, vcc, 0, v15, vcc
	v_add_co_u32_e32 v22, vcc, s28, v16
	global_load_dword v108, v[26:27], off offset:3072
	s_nop 0
	global_load_dword v109, v[14:15], off offset:1024
	v_addc_co_u32_e32 v23, vcc, 0, v17, vcc
	v_add_co_u32_e32 v14, vcc, s29, v16
	global_load_dword v110, v[22:23], off offset:3072
	s_nop 0
	v_addc_co_u32_e32 v15, vcc, 0, v17, vcc
	v_add_co_u32_e32 v16, vcc, s30, v18
	s_add_u32 s16, s16, 0x800
	s_nop 0
	v_addc_co_u32_e32 v17, vcc, 0, v19, vcc
	v_add_co_u32_e32 v22, vcc, s31, v18
	global_load_dword v111, v[16:17], off offset:3072
	s_nop 0
	v_addc_co_u32_e32 v23, vcc, 0, v19, vcc
	v_add_co_u32_e32 v16, vcc, s34, v18
	s_addc_u32 s17, s17, 0
	s_nop 0
	v_addc_co_u32_e32 v17, vcc, 0, v19, vcc
	v_add_co_u32_e32 v18, vcc, s30, v20
	global_load_dword v112, v[22:23], off offset:1024
	s_nop 0
	global_load_dword v113, v[16:17], off offset:3072
	v_addc_co_u32_e32 v19, vcc, 0, v21, vcc
	global_load_dword v114, v[18:19], off offset:3072
	s_nop 0
	global_load_dword v115, v[14:15], off offset:1024
	v_and_or_b32 v15, v1, s35, v10
	v_add_u32_e32 v14, s41, v8
	v_lshlrev_b32_e32 v8, 1, v15
	v_ashrrev_i32_e32 v15, 31, v14
	v_lshlrev_b64 v[14:15], 15, v[14:15]
	v_lshl_add_u64 v[14:15], s[12:13], 0, v[14:15]
	v_lshl_add_u64 v[14:15], v[14:15], 0, v[8:9]
	v_add_u32_e32 v19, 0x200, v12
	v_mov_b32_e32 v12, v19
	s_add_u32 s22, s22, 0x800
	s_addc_u32 s23, s23, 0
	s_add_u32 s20, s20, 0x800
	s_addc_u32 s21, s21, 0
	v_add_u32_e32 v1, 0x2000, v1
	v_mov_b32_e32 v116, v14
	v_mov_b32_e32 v117, v15
	v_lshl_add_u64 v[14:15], s[14:15], 0, v[2:3]
	v_add_co_u32_e32 v22, vcc, 0x1e200000, v14
; __device__ __forceinline__ void ffn_fixup(int pm, const float* __restrict__ UH, const float* __restrict__ UT, const float* __restrict__ cw, const float* __restrict__ cb, bf16_t* __restrict__ ACT, int tid) {
;     ...
;     for (int f = tid; f < FF; f += 512) {
;         float cva[2], cvg[2];
; #pragma unroll
;         for (int hg = 0; hg < 2; ++hg) {
;             const int ch = hg * FF + f;
;             const float h0 = UH[(size_t)(pm * 2 + 0) * FF2 + ch], h1 = UH[(size_t)(pm * 2 + 1) * FF2 + ch];
;             const float q2 = UT[(size_t)((pm - 1) * 2 + 0) * FF2 + ch], q1 = UT[(size_t)((pm - 1) * 2 + 1) * FF2 + ch];
;             const float w0 = cw[ch], w1 = cw[FF2 + ch], w2 = cw[2 * FF2 + ch], bb = cb[ch];
	v_lshl_add_u64 v[16:17], s[16:17], 0, v[2:3]
	s_nop 0
	v_addc_co_u32_e32 v23, vcc, 0, v15, vcc
	v_add_co_u32_e32 v24, vcc, 0x1e205000, v14
	v_lshl_add_u64 v[18:19], s[22:23], 0, v[2:3]
	s_nop 0
	v_addc_co_u32_e32 v25, vcc, 0, v15, vcc
	v_add_co_u32_e32 v26, vcc, 0x1ea00000, v16
	v_lshl_add_u64 v[20:21], s[20:21], 0, v[2:3]
	s_nop 0
	v_addc_co_u32_e32 v27, vcc, 0, v17, vcc
	global_load_dword v120, v[18:19], off
	global_load_dword v121, v[20:21], off
	global_load_dword v122, v[22:23], off
	global_load_dword v123, v[24:25], off offset:2048
	v_add_co_u32_e32 v22, vcc, 0x1ea05000, v16
	v_ashrrev_i32_e32 v8, 6, v12
	s_nop 0
	v_addc_co_u32_e32 v23, vcc, 0, v17, vcc
	v_add_co_u32_e32 v24, vcc, 0x5000, v18
	global_load_dword v124, v[26:27], off
	global_load_dword v125, v[22:23], off offset:2048
	v_addc_co_u32_e32 v25, vcc, 0, v19, vcc
	v_add_co_u32_e32 v22, vcc, s25, v18
	s_add_u32 s14, s14, 0x800
	s_nop 0
	v_addc_co_u32_e32 v23, vcc, 0, v19, vcc
	v_add_co_u32_e32 v26, vcc, s26, v14
	global_load_dword v126, v[24:25], off offset:2048
	s_nop 0
	global_load_dword v127, v[22:23], off
	v_addc_co_u32_e32 v27, vcc, 0, v15, vcc
	v_add_co_u32_e32 v14, vcc, s27, v14
	s_addc_u32 s15, s15, 0
	s_nop 0
	v_addc_co_u32_e32 v15, vcc, 0, v15, vcc
	v_add_co_u32_e32 v22, vcc, s28, v16
	global_load_dword v128, v[26:27], off offset:3072
	s_nop 0
	global_load_dword v129, v[14:15], off offset:1024
	v_addc_co_u32_e32 v23, vcc, 0, v17, vcc
	v_add_co_u32_e32 v14, vcc, s29, v16
	global_load_dword v130, v[22:23], off offset:3072
	s_nop 0
	v_addc_co_u32_e32 v15, vcc, 0, v17, vcc
	v_add_co_u32_e32 v16, vcc, s30, v18
	s_add_u32 s16, s16, 0x800
	s_nop 0
	v_addc_co_u32_e32 v17, vcc, 0, v19, vcc
	v_add_co_u32_e32 v22, vcc, s31, v18
	global_load_dword v131, v[16:17], off offset:3072
	s_nop 0
	v_addc_co_u32_e32 v23, vcc, 0, v19, vcc
	v_add_co_u32_e32 v16, vcc, s34, v18
	s_addc_u32 s17, s17, 0
	s_nop 0
	v_addc_co_u32_e32 v17, vcc, 0, v19, vcc
	v_add_co_u32_e32 v18, vcc, s30, v20
	global_load_dword v132, v[22:23], off offset:1024
	s_nop 0
	global_load_dword v133, v[16:17], off offset:3072
	v_addc_co_u32_e32 v19, vcc, 0, v21, vcc
	global_load_dword v134, v[18:19], off offset:3072
	s_nop 0
	global_load_dword v135, v[14:15], off offset:1024
	v_and_or_b32 v15, v1, s35, v10
	v_add_u32_e32 v14, s41, v8
	v_lshlrev_b32_e32 v8, 1, v15
	v_ashrrev_i32_e32 v15, 31, v14
	v_lshlrev_b64 v[14:15], 15, v[14:15]
	v_lshl_add_u64 v[14:15], s[12:13], 0, v[14:15]
	v_lshl_add_u64 v[14:15], v[14:15], 0, v[8:9]
	v_add_u32_e32 v19, 0x200, v12
	v_mov_b32_e32 v12, v19
	s_add_u32 s22, s22, 0x800
	s_addc_u32 s23, s23, 0
	s_add_u32 s20, s20, 0x800
	s_addc_u32 s21, s21, 0
	v_add_u32_e32 v1, 0x2000, v1
	v_mov_b32_e32 v136, v14
	v_mov_b32_e32 v137, v15
	s_nop 0
	v_readfirstlane_b32 s18, v12
	s_cmpk_gt_i32 s18, 0xaff
	s_cbranch_scc1 .Lfx0_issued
	v_lshl_add_u64 v[14:15], s[14:15], 0, v[2:3]
	v_add_co_u32_e32 v22, vcc, 0x1e200000, v14
	v_lshl_add_u64 v[16:17], s[16:17], 0, v[2:3]
	s_nop 0
	v_addc_co_u32_e32 v23, vcc, 0, v15, vcc
	v_add_co_u32_e32 v24, vcc, 0x1e205000, v14
	v_lshl_add_u64 v[18:19], s[22:23], 0, v[2:3]
	s_nop 0
	v_addc_co_u32_e32 v25, vcc, 0, v15, vcc
	v_add_co_u32_e32 v26, vcc, 0x1ea00000, v16
	v_lshl_add_u64 v[20:21], s[20:21], 0, v[2:3]
	s_nop 0
	v_addc_co_u32_e32 v27, vcc, 0, v17, vcc
	global_load_dword v140, v[18:19], off
	global_load_dword v141, v[20:21], off
	global_load_dword v142, v[22:23], off
	global_load_dword v143, v[24:25], off offset:2048
	v_add_co_u32_e32 v22, vcc, 0x1ea05000, v16
	v_ashrrev_i32_e32 v8, 6, v12
	s_nop 0
	v_addc_co_u32_e32 v23, vcc, 0, v17, vcc
	v_add_co_u32_e32 v24, vcc, 0x5000, v18
	global_load_dword v144, v[26:27], off
	global_load_dword v145, v[22:23], off offset:2048
	v_addc_co_u32_e32 v25, vcc, 0, v19, vcc
	v_add_co_u32_e32 v22, vcc, s25, v18
	s_add_u32 s14, s14, 0x800
	s_nop 0
	v_addc_co_u32_e32 v23, vcc, 0, v19, vcc
	v_add_co_u32_e32 v26, vcc, s26, v14
	global_load_dword v146, v[24:25], off offset:2048
	s_nop 0
	global_load_dword v147, v[22:23], off
	v_addc_co_u32_e32 v27, vcc, 0, v15, vcc
	v_add_co_u32_e32 v14, vcc, s27, v14
	s_addc_u32 s15, s15, 0
	s_nop 0
	v_addc_co_u32_e32 v15, vcc, 0, v15, vcc
	v_add_co_u32_e32 v22, vcc, s28, v16
	global_load_dword v148, v[26:27], off offset:3072
	s_nop 0
	global_load_dword v149, v[14:15], off offset:1024
	v_addc_co_u32_e32 v23, vcc, 0, v17, vcc
	v_add_co_u32_e32 v14, vcc, s29, v16
	global_load_dword v150, v[22:23], off offset:3072
	s_nop 0
	v_addc_co_u32_e32 v15, vcc, 0, v17, vcc
	v_add_co_u32_e32 v16, vcc, s30, v18
	s_add_u32 s16, s16, 0x800
	s_nop 0
	v_addc_co_u32_e32 v17, vcc, 0, v19, vcc
	v_add_co_u32_e32 v22, vcc, s31, v18
	global_load_dword v151, v[16:17], off offset:3072
	s_nop 0
	v_addc_co_u32_e32 v23, vcc, 0, v19, vcc
	v_add_co_u32_e32 v16, vcc, s34, v18
	s_addc_u32 s17, s17, 0
	s_nop 0
	v_addc_co_u32_e32 v17, vcc, 0, v19, vcc
	v_add_co_u32_e32 v18, vcc, s30, v20
	global_load_dword v152, v[22:23], off offset:1024
	s_nop 0
	global_load_dword v153, v[16:17], off offset:3072
	v_addc_co_u32_e32 v19, vcc, 0, v21, vcc
	global_load_dword v154, v[18:19], off offset:3072
	s_nop 0
	global_load_dword v155, v[14:15], off offset:1024
	v_and_or_b32 v15, v1, s35, v10
	v_add_u32_e32 v14, s41, v8
	v_lshlrev_b32_e32 v8, 1, v15
	v_ashrrev_i32_e32 v15, 31, v14
	v_lshlrev_b64 v[14:15], 15, v[14:15]
	v_lshl_add_u64 v[14:15], s[12:13], 0, v[14:15]
	v_lshl_add_u64 v[14:15], v[14:15], 0, v[8:9]
	v_add_u32_e32 v19, 0x200, v12
	v_mov_b32_e32 v12, v19
	s_add_u32 s22, s22, 0x800
	s_addc_u32 s23, s23, 0
	s_add_u32 s20, s20, 0x800
	s_addc_u32 s21, s21, 0
	v_add_u32_e32 v1, 0x2000, v1
	v_mov_b32_e32 v156, v14
	v_mov_b32_e32 v157, v15
; __device__ __forceinline__ unsigned f2bf(float f) { unsigned u = __builtin_bit_cast(unsigned, f); return (u + 0x7fffu + ((u >> 16) & 1u)) >> 16; }
; __device__ __forceinline__ void ffn_fixup(int pm, const float* __restrict__ UH, const float* __restrict__ UT, const float* __restrict__ cw, const float* __restrict__ cb, bf16_t* __restrict__ ACT, int tid) {
;     ...
;             const float r0 = bb + w2 * h0 + w1 * q1 + w0 * q2, r1 = bb + w2 * h1 + w1 * h0 + w0 * q1;
;             if (hg == 0) { cva[0] = r0; cva[1] = r1; } else { cvg[0] = r0; cvg[1] = r1; }
;         }
; #pragma unroll
;         for (int r = 0; r < 2; ++r) { const float a = cva[r]; const float y = a * __builtin_amdgcn_rcpf(1.0f + __builtin_amdgcn_exp2f(-a * LOG2E)) * cvg[r];
;             ACT[pg8::aimg_off(pm * 256 + r, f, FF / 64)] = (bf16_t)f2bf(y); }
; __global__ void __launch_bounds__(512, 2) hybrid_fwd(Args args) {
;     ...
;           asm volatile("s_waitcnt vmcnt(0)" ::: "memory"); __syncthreads(); }
;         EpiRes<false> E{XB, out, SSQ + 2 * SSQ_STRIDE};
;         pg8::gemm_phase<EpiRes<false>, true>(lds, g, S, E);
.Lfx0_issued:
	s_waitcnt vmcnt(0)
	v_fma_f32 v8, v42, v47, v41
	v_fmac_f32_e32 v41, v43, v47
	v_fmac_f32_e32 v8, v45, v46
	v_fmac_f32_e32 v41, v42, v46
	v_fmac_f32_e32 v8, v44, v40
	v_fmac_f32_e32 v41, v45, v40
	v_mul_f32_e32 v40, 0xbfb8aa3b, v8
	v_mul_f32_e32 v19, 0xbfb8aa3b, v41
	v_exp_f32_e32 v40, v40
	v_exp_f32_e32 v19, v19
	v_add_f32_e32 v40, 1.0, v40
	v_rcp_f32_e32 v40, v40
	v_fma_f32 v21, v48, v53, v54
	v_fmac_f32_e32 v54, v49, v53
	v_add_f32_e32 v53, 1.0, v19
	v_rcp_f32_e32 v53, v53
	v_fmac_f32_e32 v21, v55, v52
	v_fmac_f32_e32 v54, v48, v52
	v_fmac_f32_e32 v21, v50, v51
	v_mul_f32_e32 v8, v8, v40
	v_fmac_f32_e32 v54, v55, v51
	v_mul_f32_e32 v40, v41, v53
	v_mul_f32_e32 v8, v8, v21
	v_mul_f32_e32 v40, v40, v54
	v_bfe_u32 v53, v8, 16, 1
	v_bfe_u32 v54, v40, 16, 1
	v_add3_u32 v8, v8, v53, s38
	v_add3_u32 v40, v40, v54, s38
	global_store_short_d16_hi v[56:57], v8, off
	global_store_short_d16_hi v[56:57], v40, off offset:64
	v_fma_f32 v8, v62, v67, v61
	v_fmac_f32_e32 v61, v63, v67
	v_fmac_f32_e32 v8, v65, v66
	v_fmac_f32_e32 v61, v62, v66
	v_fmac_f32_e32 v8, v64, v60
	v_fmac_f32_e32 v61, v65, v60
	v_mul_f32_e32 v60, 0xbfb8aa3b, v8
	v_mul_f32_e32 v19, 0xbfb8aa3b, v61
	v_exp_f32_e32 v60, v60
	v_exp_f32_e32 v19, v19
	v_add_f32_e32 v60, 1.0, v60
	v_rcp_f32_e32 v60, v60
	v_fma_f32 v21, v68, v73, v74
	v_fmac_f32_e32 v74, v69, v73
	v_add_f32_e32 v73, 1.0, v19
	v_rcp_f32_e32 v73, v73
	v_fmac_f32_e32 v21, v75, v72
	v_fmac_f32_e32 v74, v68, v72
	v_fmac_f32_e32 v21, v70, v71
	v_mul_f32_e32 v8, v8, v60
	v_fmac_f32_e32 v74, v75, v71
	v_mul_f32_e32 v60, v61, v73
	v_mul_f32_e32 v8, v8, v21
	v_mul_f32_e32 v60, v60, v74
	v_bfe_u32 v73, v8, 16, 1
	v_bfe_u32 v74, v60, 16, 1
	v_add3_u32 v8, v8, v73, s38
	v_add3_u32 v60, v60, v74, s38
	global_store_short_d16_hi v[76:77], v8, off
	global_store_short_d16_hi v[76:77], v60, off offset:64
	v_fma_f32 v8, v82, v87, v81
	v_fmac_f32_e32 v81, v83, v87
	v_fmac_f32_e32 v8, v85, v86
	v_fmac_f32_e32 v81, v82, v86
	v_fmac_f32_e32 v8, v84, v80
	v_fmac_f32_e32 v81, v85, v80
	v_mul_f32_e32 v80, 0xbfb8aa3b, v8
	v_mul_f32_e32 v19, 0xbfb8aa3b, v81
	v_exp_f32_e32 v80, v80
	v_exp_f32_e32 v19, v19
	v_add_f32_e32 v80, 1.0, v80
	v_rcp_f32_e32 v80, v80
	v_fma_f32 v21, v88, v93, v94
	v_fmac_f32_e32 v94, v89, v93
	v_add_f32_e32 v93, 1.0, v19
	v_rcp_f32_e32 v93, v93
	v_fmac_f32_e32 v21, v95, v92
	v_fmac_f32_e32 v94, v88, v92
	v_fmac_f32_e32 v21, v90, v91
	v_mul_f32_e32 v8, v8, v80
	v_fmac_f32_e32 v94, v95, v91
	v_mul_f32_e32 v80, v81, v93
	v_mul_f32_e32 v8, v8, v21
	v_mul_f32_e32 v80, v80, v94
	v_bfe_u32 v93, v8, 16, 1
	v_bfe_u32 v94, v80, 16, 1
	v_add3_u32 v8, v8, v93, s38
	v_add3_u32 v80, v80, v94, s38
	global_store_short_d16_hi v[96:97], v8, off
	global_store_short_d16_hi v[96:97], v80, off offset:64
	v_fma_f32 v8, v102, v107, v101
	v_fmac_f32_e32 v101, v103, v107
	v_fmac_f32_e32 v8, v105, v106
	v_fmac_f32_e32 v101, v102, v106
	v_fmac_f32_e32 v8, v104, v100
	v_fmac_f32_e32 v101, v105, v100
	v_mul_f32_e32 v100, 0xbfb8aa3b, v8
	v_mul_f32_e32 v19, 0xbfb8aa3b, v101
	v_exp_f32_e32 v100, v100
	v_exp_f32_e32 v19, v19
	v_add_f32_e32 v100, 1.0, v100
	v_rcp_f32_e32 v100, v100
	v_fma_f32 v21, v108, v113, v114
	v_fmac_f32_e32 v114, v109, v113
	v_add_f32_e32 v113, 1.0, v19
	v_rcp_f32_e32 v113, v113
	v_fmac_f32_e32 v21, v115, v112
	v_fmac_f32_e32 v114, v108, v112
	v_fmac_f32_e32 v21, v110, v111
	v_mul_f32_e32 v8, v8, v100
	v_fmac_f32_e32 v114, v115, v111
	v_mul_f32_e32 v100, v101, v113
	v_mul_f32_e32 v8, v8, v21
	v_mul_f32_e32 v100, v100, v114
	v_bfe_u32 v113, v8, 16, 1
	v_bfe_u32 v114, v100, 16, 1
	v_add3_u32 v8, v8, v113, s38
	v_add3_u32 v100, v100, v114, s38
	global_store_short_d16_hi v[116:117], v8, off
	global_store_short_d16_hi v[116:117], v100, off offset:64
	v_fma_f32 v8, v122, v127, v121
	v_fmac_f32_e32 v121, v123, v127
	v_fmac_f32_e32 v8, v125, v126
	v_fmac_f32_e32 v121, v122, v126
	v_fmac_f32_e32 v8, v124, v120
	v_fmac_f32_e32 v121, v125, v120
	v_mul_f32_e32 v120, 0xbfb8aa3b, v8
	v_mul_f32_e32 v19, 0xbfb8aa3b, v121
	v_exp_f32_e32 v120, v120
	v_exp_f32_e32 v19, v19
	v_add_f32_e32 v120, 1.0, v120
	v_rcp_f32_e32 v120, v120
	v_fma_f32 v21, v128, v133, v134
	v_fmac_f32_e32 v134, v129, v133
	v_add_f32_e32 v133, 1.0, v19
	v_rcp_f32_e32 v133, v133
	v_fmac_f32_e32 v21, v135, v132
	v_fmac_f32_e32 v134, v128, v132
	v_fmac_f32_e32 v21, v130, v131
	v_mul_f32_e32 v8, v8, v120
	v_fmac_f32_e32 v134, v135, v131
	v_mul_f32_e32 v120, v121, v133
	v_mul_f32_e32 v8, v8, v21
	v_mul_f32_e32 v120, v120, v134
	v_bfe_u32 v133, v8, 16, 1
	v_bfe_u32 v134, v120, 16, 1
	v_add3_u32 v8, v8, v133, s38
	v_add3_u32 v120, v120, v134, s38
	global_store_short_d16_hi v[136:137], v8, off
	global_store_short_d16_hi v[136:137], v120, off offset:64
	s_cmpk_gt_i32 s18, 0xaff
	s_cbranch_scc1 .Lfx0_done
	v_fma_f32 v8, v142, v147, v141
	v_fmac_f32_e32 v141, v143, v147
	v_fmac_f32_e32 v8, v145, v146
	v_fmac_f32_e32 v141, v142, v146
	v_fmac_f32_e32 v8, v144, v140
	v_fmac_f32_e32 v141, v145, v140
	v_mul_f32_e32 v140, 0xbfb8aa3b, v8
	v_mul_f32_e32 v19, 0xbfb8aa3b, v141
	v_exp_f32_e32 v140, v140
	v_exp_f32_e32 v19, v19
	v_add_f32_e32 v140, 1.0, v140
	v_rcp_f32_e32 v140, v140
	v_fma_f32 v21, v148, v153, v154
	v_fmac_f32_e32 v154, v149, v153
	v_add_f32_e32 v153, 1.0, v19
	v_rcp_f32_e32 v153, v153
	v_fmac_f32_e32 v21, v155, v152
	v_fmac_f32_e32 v154, v148, v152
	v_fmac_f32_e32 v21, v150, v151
	v_mul_f32_e32 v8, v8, v140
	v_fmac_f32_e32 v154, v155, v151
	v_mul_f32_e32 v140, v141, v153
	v_mul_f32_e32 v8, v8, v21
	v_mul_f32_e32 v140, v140, v154
	v_bfe_u32 v153, v8, 16, 1
	v_bfe_u32 v154, v140, 16, 1
	v_add3_u32 v8, v8, v153, s38
	v_add3_u32 v140, v140, v154, s38
	global_store_short_d16_hi v[156:157], v8, off
	global_store_short_d16_hi v[156:157], v140, off offset:64
.Lfx0_done:
	s_branch .LBB0_692
.LBB0_704:
	s_waitcnt vmcnt(0)
	v_mov_b32_e32 v0, v220
	s_cmpk_lt_i32 s2, 0x200
	s_waitcnt vmcnt(0)
	s_barrier
	s_cselect_b64 s[6:7], -1, 0
	s_cmpk_gt_i32 s2, 0x1ff
	v_readfirstlane_b32 s20, v0
	s_cbranch_scc1 .LBB0_710
	s_ashr_i32 s8, s2, 31
	s_lshr_b32 s8, s8, 29
	s_add_i32 s16, s2, s8
	s_and_b32 s8, s16, -8
	s_sub_i32 s14, s2, s8
	s_cmp_gt_i32 s14, -1
	s_cbranch_scc0 .LBB0_707
	s_lshl_b32 s15, s14, 6
	s_ashr_i32 s8, s16, 3
	s_cbranch_execz .LBB0_708
	s_branch .LBB0_709

; __device__ __forceinline__ void ffn_fixup(int pm, const float* __restrict__ UH, const float* __restrict__ UT, const float* __restrict__ cw, const float* __restrict__ cb, bf16_t* __restrict__ ACT, int tid) {
;     ...
;     for (int f = tid; f < FF; f += 512) {
;         float cva[2], cvg[2];
; #pragma unroll
;         for (int hg = 0; hg < 2; ++hg) {
;             const int ch = hg * FF + f;
;             const float h0 = UH[(size_t)(pm * 2 + 0) * FF2 + ch], h1 = UH[(size_t)(pm * 2 + 1) * FF2 + ch];
;             const float q2 = UT[(size_t)((pm - 1) * 2 + 0) * FF2 + ch], q1 = UT[(size_t)((pm - 1) * 2 + 1) * FF2 + ch];
;             const float w0 = cw[ch], w1 = cw[FF2 + ch], w2 = cw[2 * FF2 + ch], bb = cb[ch];
.LBB0_1385:
	v_lshl_add_u64 v[14:15], s[8:9], 0, v[2:3]
	v_add_co_u32_e32 v22, vcc, 0x1e200000, v14
	v_lshl_add_u64 v[16:17], s[10:11], 0, v[2:3]
	s_nop 0
	v_addc_co_u32_e32 v23, vcc, 0, v15, vcc
	v_add_co_u32_e32 v24, vcc, 0x1e205000, v14
	v_lshl_add_u64 v[18:19], s[16:17], 0, v[2:3]
	s_nop 0
	v_addc_co_u32_e32 v25, vcc, 0, v15, vcc
	v_add_co_u32_e32 v26, vcc, 0x1ea00000, v16
	global_load_dword v40, v[22:23], off
	global_load_dword v41, v[24:25], off offset:2048
	v_addc_co_u32_e32 v27, vcc, 0, v17, vcc
	v_add_co_u32_e32 v22, vcc, 0x1ea05000, v16
	v_lshl_add_u64 v[20:21], s[14:15], 0, v[2:3]
	s_nop 0
	v_addc_co_u32_e32 v23, vcc, 0, v17, vcc
	v_add_co_u32_e32 v24, vcc, 0x10000, v18
	global_load_dword v42, v[26:27], off
	global_load_dword v43, v[22:23], off offset:2048
	v_addc_co_u32_e32 v25, vcc, 0, v19, vcc
	v_add_co_u32_e32 v22, vcc, 0x16000, v18
	global_load_dword v44, v[24:25], off offset:2048
	s_nop 0
	v_addc_co_u32_e32 v23, vcc, 0, v19, vcc
	v_add_co_u32_e32 v24, vcc, 0x1b000, v18
	v_ashrrev_i32_e32 v8, 6, v12
	s_nop 0
	v_addc_co_u32_e32 v25, vcc, 0, v19, vcc
	v_add_co_u32_e32 v26, vcc, 0x5000, v20
	global_load_dword v45, v[22:23], off
	global_load_dword v46, v[24:25], off offset:2048
	v_addc_co_u32_e32 v27, vcc, 0, v21, vcc
	v_add_co_u32_e32 v22, vcc, 0x1e202000, v14
	global_load_dword v47, v[26:27], off offset:2048
	s_nop 0
	v_addc_co_u32_e32 v23, vcc, 0, v15, vcc
	v_add_co_u32_e32 v14, vcc, 0x1e208000, v14
	s_add_u32 s8, s8, 0x800
	s_nop 0
	v_addc_co_u32_e32 v15, vcc, 0, v15, vcc
	v_add_co_u32_e32 v24, vcc, 0x1ea02000, v16
	global_load_dword v48, v[22:23], off offset:3072
	global_load_dword v49, v[14:15], off offset:1024
	v_addc_co_u32_e32 v25, vcc, 0, v17, vcc
	v_add_co_u32_e32 v14, vcc, 0x1ea08000, v16
	global_load_dword v50, v[24:25], off offset:3072
	s_nop 0
	v_addc_co_u32_e32 v15, vcc, 0, v17, vcc
	v_add_co_u32_e32 v16, vcc, 0x13000, v18
	s_addc_u32 s9, s9, 0
	s_nop 0
	v_addc_co_u32_e32 v17, vcc, 0, v19, vcc
	v_add_co_u32_e32 v22, vcc, 0x18000, v18
	global_load_dword v51, v[16:17], off offset:1024
	s_nop 0
	v_addc_co_u32_e32 v23, vcc, 0, v19, vcc
	v_add_co_u32_e32 v16, vcc, 0x1e000, v18
	s_add_u32 s10, s10, 0x800
	s_nop 0
	v_addc_co_u32_e32 v17, vcc, 0, v19, vcc
	v_add_co_u32_e32 v18, vcc, 0x8000, v20
	global_load_dword v52, v[22:23], off offset:3072
	global_load_dword v53, v[16:17], off offset:1024
	v_addc_co_u32_e32 v19, vcc, 0, v21, vcc
	global_load_dword v54, v[18:19], off offset:1024
	global_load_dword v55, v[14:15], off offset:1024
	v_and_or_b32 v15, v1, s19, v10
	v_add_u32_e32 v14, s23, v8
	v_lshlrev_b32_e32 v8, 1, v15
	v_ashrrev_i32_e32 v15, 31, v14
	v_lshlrev_b64 v[14:15], 15, v[14:15]
	v_lshl_add_u64 v[14:15], s[6:7], 0, v[14:15]
	v_lshl_add_u64 v[14:15], v[14:15], 0, v[8:9]
	v_add_u32_e32 v18, 0x200, v12
	v_mov_b32_e32 v12, v18
	s_addc_u32 s11, s11, 0
	s_add_u32 s16, s16, 0x800
	s_addc_u32 s17, s17, 0
	s_add_u32 s14, s14, 0x800
	s_addc_u32 s15, s15, 0
	v_add_u32_e32 v1, 0x2000, v1
	v_mov_b32_e32 v56, v14
	v_mov_b32_e32 v57, v15
	v_lshl_add_u64 v[14:15], s[8:9], 0, v[2:3]
	v_add_co_u32_e32 v22, vcc, 0x1e200000, v14
	v_lshl_add_u64 v[16:17], s[10:11], 0, v[2:3]
	s_nop 0
	v_addc_co_u32_e32 v23, vcc, 0, v15, vcc
	v_add_co_u32_e32 v24, vcc, 0x1e205000, v14
	v_lshl_add_u64 v[18:19], s[16:17], 0, v[2:3]
	s_nop 0
	v_addc_co_u32_e32 v25, vcc, 0, v15, vcc
	v_add_co_u32_e32 v26, vcc, 0x1ea00000, v16
	global_load_dword v60, v[22:23], off
	global_load_dword v61, v[24:25], off offset:2048
	v_addc_co_u32_e32 v27, vcc, 0, v17, vcc
	v_add_co_u32_e32 v22, vcc, 0x1ea05000, v16
	v_lshl_add_u64 v[20:21], s[14:15], 0, v[2:3]
	s_nop 0
	v_addc_co_u32_e32 v23, vcc, 0, v17, vcc
	v_add_co_u32_e32 v24, vcc, 0x10000, v18
	global_load_dword v62, v[26:27], off
	global_load_dword v63, v[22:23], off offset:2048
	v_addc_co_u32_e32 v25, vcc, 0, v19, vcc
	v_add_co_u32_e32 v22, vcc, 0x16000, v18
	global_load_dword v64, v[24:25], off offset:2048
	s_nop 0
	v_addc_co_u32_e32 v23, vcc, 0, v19, vcc
	v_add_co_u32_e32 v24, vcc, 0x1b000, v18
	v_ashrrev_i32_e32 v8, 6, v12
	s_nop 0
	v_addc_co_u32_e32 v25, vcc, 0, v19, vcc
	v_add_co_u32_e32 v26, vcc, 0x5000, v20
	global_load_dword v65, v[22:23], off
	global_load_dword v66, v[24:25], off offset:2048
	v_addc_co_u32_e32 v27, vcc, 0, v21, vcc
	v_add_co_u32_e32 v22, vcc, 0x1e202000, v14
	global_load_dword v67, v[26:27], off offset:2048
	s_nop 0
	v_addc_co_u32_e32 v23, vcc, 0, v15, vcc
	v_add_co_u32_e32 v14, vcc, 0x1e208000, v14
	s_add_u32 s8, s8, 0x800
	s_nop 0
	v_addc_co_u32_e32 v15, vcc, 0, v15, vcc
	v_add_co_u32_e32 v24, vcc, 0x1ea02000, v16
	global_load_dword v68, v[22:23], off offset:3072
	global_load_dword v69, v[14:15], off offset:1024
	v_addc_co_u32_e32 v25, vcc, 0, v17, vcc
	v_add_co_u32_e32 v14, vcc, 0x1ea08000, v16
	global_load_dword v70, v[24:25], off offset:3072
	s_nop 0
	v_addc_co_u32_e32 v15, vcc, 0, v17, vcc
	v_add_co_u32_e32 v16, vcc, 0x13000, v18
	s_addc_u32 s9, s9, 0
	s_nop 0
	v_addc_co_u32_e32 v17, vcc, 0, v19, vcc
	v_add_co_u32_e32 v22, vcc, 0x18000, v18
	global_load_dword v71, v[16:17], off offset:1024
	s_nop 0
	v_addc_co_u32_e32 v23, vcc, 0, v19, vcc
	v_add_co_u32_e32 v16, vcc, 0x1e000, v18
	s_add_u32 s10, s10, 0x800
	s_nop 0
	v_addc_co_u32_e32 v17, vcc, 0, v19, vcc
	v_add_co_u32_e32 v18, vcc, 0x8000, v20
	global_load_dword v72, v[22:23], off offset:3072
	global_load_dword v73, v[16:17], off offset:1024
	v_addc_co_u32_e32 v19, vcc, 0, v21, vcc
	global_load_dword v74, v[18:19], off offset:1024
	global_load_dword v75, v[14:15], off offset:1024
	v_and_or_b32 v15, v1, s19, v10
	v_add_u32_e32 v14, s23, v8
	v_lshlrev_b32_e32 v8, 1, v15
	v_ashrrev_i32_e32 v15, 31, v14
	v_lshlrev_b64 v[14:15], 15, v[14:15]
; __device__ __forceinline__ void ffn_fixup(int pm, const float* __restrict__ UH, const float* __restrict__ UT, const float* __restrict__ cw, const float* __restrict__ cb, bf16_t* __restrict__ ACT, int tid) {
;     ...
;     for (int f = tid; f < FF; f += 512) {
;         float cva[2], cvg[2];
; #pragma unroll
;         for (int hg = 0; hg < 2; ++hg) {
;             const int ch = hg * FF + f;
;             const float h0 = UH[(size_t)(pm * 2 + 0) * FF2 + ch], h1 = UH[(size_t)(pm * 2 + 1) * FF2 + ch];
;             const float q2 = UT[(size_t)((pm - 1) * 2 + 0) * FF2 + ch], q1 = UT[(size_t)((pm - 1) * 2 + 1) * FF2 + ch];
;             const float w0 = cw[ch], w1 = cw[FF2 + ch], w2 = cw[2 * FF2 + ch], bb = cb[ch];
	v_lshl_add_u64 v[14:15], s[6:7], 0, v[14:15]
	v_lshl_add_u64 v[14:15], v[14:15], 0, v[8:9]
	v_add_u32_e32 v18, 0x200, v12
	v_mov_b32_e32 v12, v18
	s_addc_u32 s11, s11, 0
	s_add_u32 s16, s16, 0x800
	s_addc_u32 s17, s17, 0
	s_add_u32 s14, s14, 0x800
	s_addc_u32 s15, s15, 0
	v_add_u32_e32 v1, 0x2000, v1
	v_mov_b32_e32 v76, v14
	v_mov_b32_e32 v77, v15
	v_lshl_add_u64 v[14:15], s[8:9], 0, v[2:3]
	v_add_co_u32_e32 v22, vcc, 0x1e200000, v14
	v_lshl_add_u64 v[16:17], s[10:11], 0, v[2:3]
	s_nop 0
	v_addc_co_u32_e32 v23, vcc, 0, v15, vcc
	v_add_co_u32_e32 v24, vcc, 0x1e205000, v14
	v_lshl_add_u64 v[18:19], s[16:17], 0, v[2:3]
	s_nop 0
	v_addc_co_u32_e32 v25, vcc, 0, v15, vcc
	v_add_co_u32_e32 v26, vcc, 0x1ea00000, v16
	global_load_dword v80, v[22:23], off
	global_load_dword v81, v[24:25], off offset:2048
	v_addc_co_u32_e32 v27, vcc, 0, v17, vcc
	v_add_co_u32_e32 v22, vcc, 0x1ea05000, v16
	v_lshl_add_u64 v[20:21], s[14:15], 0, v[2:3]
	s_nop 0
	v_addc_co_u32_e32 v23, vcc, 0, v17, vcc
	v_add_co_u32_e32 v24, vcc, 0x10000, v18
	global_load_dword v82, v[26:27], off
	global_load_dword v83, v[22:23], off offset:2048
	v_addc_co_u32_e32 v25, vcc, 0, v19, vcc
	v_add_co_u32_e32 v22, vcc, 0x16000, v18
	global_load_dword v84, v[24:25], off offset:2048
	s_nop 0
	v_addc_co_u32_e32 v23, vcc, 0, v19, vcc
	v_add_co_u32_e32 v24, vcc, 0x1b000, v18
	v_ashrrev_i32_e32 v8, 6, v12
	s_nop 0
	v_addc_co_u32_e32 v25, vcc, 0, v19, vcc
	v_add_co_u32_e32 v26, vcc, 0x5000, v20
	global_load_dword v85, v[22:23], off
	global_load_dword v86, v[24:25], off offset:2048
	v_addc_co_u32_e32 v27, vcc, 0, v21, vcc
	v_add_co_u32_e32 v22, vcc, 0x1e202000, v14
	global_load_dword v87, v[26:27], off offset:2048
	s_nop 0
	v_addc_co_u32_e32 v23, vcc, 0, v15, vcc
	v_add_co_u32_e32 v14, vcc, 0x1e208000, v14
	s_add_u32 s8, s8, 0x800
	s_nop 0
	v_addc_co_u32_e32 v15, vcc, 0, v15, vcc
	v_add_co_u32_e32 v24, vcc, 0x1ea02000, v16
	global_load_dword v88, v[22:23], off offset:3072
	global_load_dword v89, v[14:15], off offset:1024
	v_addc_co_u32_e32 v25, vcc, 0, v17, vcc
	v_add_co_u32_e32 v14, vcc, 0x1ea08000, v16
	global_load_dword v90, v[24:25], off offset:3072
	s_nop 0
	v_addc_co_u32_e32 v15, vcc, 0, v17, vcc
	v_add_co_u32_e32 v16, vcc, 0x13000, v18
	s_addc_u32 s9, s9, 0
	s_nop 0
	v_addc_co_u32_e32 v17, vcc, 0, v19, vcc
	v_add_co_u32_e32 v22, vcc, 0x18000, v18
	global_load_dword v91, v[16:17], off offset:1024
	s_nop 0
	v_addc_co_u32_e32 v23, vcc, 0, v19, vcc
	v_add_co_u32_e32 v16, vcc, 0x1e000, v18
	s_add_u32 s10, s10, 0x800
	s_nop 0
	v_addc_co_u32_e32 v17, vcc, 0, v19, vcc
	v_add_co_u32_e32 v18, vcc, 0x8000, v20
	global_load_dword v92, v[22:23], off offset:3072
	global_load_dword v93, v[16:17], off offset:1024
	v_addc_co_u32_e32 v19, vcc, 0, v21, vcc
	global_load_dword v94, v[18:19], off offset:1024
	global_load_dword v95, v[14:15], off offset:1024
	v_and_or_b32 v15, v1, s19, v10
	v_add_u32_e32 v14, s23, v8
	v_lshlrev_b32_e32 v8, 1, v15
	v_ashrrev_i32_e32 v15, 31, v14
	v_lshlrev_b64 v[14:15], 15, v[14:15]
	v_lshl_add_u64 v[14:15], s[6:7], 0, v[14:15]
	v_lshl_add_u64 v[14:15], v[14:15], 0, v[8:9]
	v_add_u32_e32 v18, 0x200, v12
	v_mov_b32_e32 v12, v18
	s_addc_u32 s11, s11, 0
	s_add_u32 s16, s16, 0x800
	s_addc_u32 s17, s17, 0
	s_add_u32 s14, s14, 0x800
	s_addc_u32 s15, s15, 0
	v_add_u32_e32 v1, 0x2000, v1
	v_mov_b32_e32 v96, v14
	v_mov_b32_e32 v97, v15
	v_lshl_add_u64 v[14:15], s[8:9], 0, v[2:3]
	v_add_co_u32_e32 v22, vcc, 0x1e200000, v14
	v_lshl_add_u64 v[16:17], s[10:11], 0, v[2:3]
	s_nop 0
	v_addc_co_u32_e32 v23, vcc, 0, v15, vcc
	v_add_co_u32_e32 v24, vcc, 0x1e205000, v14
	v_lshl_add_u64 v[18:19], s[16:17], 0, v[2:3]
	s_nop 0
	v_addc_co_u32_e32 v25, vcc, 0, v15, vcc
	v_add_co_u32_e32 v26, vcc, 0x1ea00000, v16
	global_load_dword v100, v[22:23], off
	global_load_dword v101, v[24:25], off offset:2048
	v_addc_co_u32_e32 v27, vcc, 0, v17, vcc
	v_add_co_u32_e32 v22, vcc, 0x1ea05000, v16
	v_lshl_add_u64 v[20:21], s[14:15], 0, v[2:3]
	s_nop 0
	v_addc_co_u32_e32 v23, vcc, 0, v17, vcc
	v_add_co_u32_e32 v24, vcc, 0x10000, v18
	global_load_dword v102, v[26:27], off
	global_load_dword v103, v[22:23], off offset:2048
	v_addc_co_u32_e32 v25, vcc, 0, v19, vcc
	v_add_co_u32_e32 v22, vcc, 0x16000, v18
	global_load_dword v104, v[24:25], off offset:2048
	s_nop 0
	v_addc_co_u32_e32 v23, vcc, 0, v19, vcc
	v_add_co_u32_e32 v24, vcc, 0x1b000, v18
	v_ashrrev_i32_e32 v8, 6, v12
	s_nop 0
	v_addc_co_u32_e32 v25, vcc, 0, v19, vcc
	v_add_co_u32_e32 v26, vcc, 0x5000, v20
	global_load_dword v105, v[22:23], off
	global_load_dword v106, v[24:25], off offset:2048
	v_addc_co_u32_e32 v27, vcc, 0, v21, vcc
	v_add_co_u32_e32 v22, vcc, 0x1e202000, v14
	global_load_dword v107, v[26:27], off offset:2048
	s_nop 0
	v_addc_co_u32_e32 v23, vcc, 0, v15, vcc
	v_add_co_u32_e32 v14, vcc, 0x1e208000, v14
	s_add_u32 s8, s8, 0x800
	s_nop 0
	v_addc_co_u32_e32 v15, vcc, 0, v15, vcc
	v_add_co_u32_e32 v24, vcc, 0x1ea02000, v16
	global_load_dword v108, v[22:23], off offset:3072
	global_load_dword v109, v[14:15], off offset:1024
	v_addc_co_u32_e32 v25, vcc, 0, v17, vcc
	v_add_co_u32_e32 v14, vcc, 0x1ea08000, v16
	global_load_dword v110, v[24:25], off offset:3072
	s_nop 0
	v_addc_co_u32_e32 v15, vcc, 0, v17, vcc
	v_add_co_u32_e32 v16, vcc, 0x13000, v18
	s_addc_u32 s9, s9, 0
	s_nop 0
	v_addc_co_u32_e32 v17, vcc, 0, v19, vcc
	v_add_co_u32_e32 v22, vcc, 0x18000, v18
	global_load_dword v111, v[16:17], off offset:1024
	s_nop 0
	v_addc_co_u32_e32 v23, vcc, 0, v19, vcc
	v_add_co_u32_e32 v16, vcc, 0x1e000, v18
	s_add_u32 s10, s10, 0x800
	s_nop 0
	v_addc_co_u32_e32 v17, vcc, 0, v19, vcc
	v_add_co_u32_e32 v18, vcc, 0x8000, v20
	global_load_dword v112, v[22:23], off offset:3072
; __device__ __forceinline__ void ffn_fixup(int pm, const float* __restrict__ UH, const float* __restrict__ UT, const float* __restrict__ cw, const float* __restrict__ cb, bf16_t* __restrict__ ACT, int tid) {
;     ...
;     for (int f = tid; f < FF; f += 512) {
;         float cva[2], cvg[2];
; #pragma unroll
;         for (int hg = 0; hg < 2; ++hg) {
;             const int ch = hg * FF + f;
;             const float h0 = UH[(size_t)(pm * 2 + 0) * FF2 + ch], h1 = UH[(size_t)(pm * 2 + 1) * FF2 + ch];
;             const float q2 = UT[(size_t)((pm - 1) * 2 + 0) * FF2 + ch], q1 = UT[(size_t)((pm - 1) * 2 + 1) * FF2 + ch];
;             const float w0 = cw[ch], w1 = cw[FF2 + ch], w2 = cw[2 * FF2 + ch], bb = cb[ch];
	global_load_dword v113, v[16:17], off offset:1024
	v_addc_co_u32_e32 v19, vcc, 0, v21, vcc
	global_load_dword v114, v[18:19], off offset:1024
	global_load_dword v115, v[14:15], off offset:1024
	v_and_or_b32 v15, v1, s19, v10
	v_add_u32_e32 v14, s23, v8
	v_lshlrev_b32_e32 v8, 1, v15
	v_ashrrev_i32_e32 v15, 31, v14
	v_lshlrev_b64 v[14:15], 15, v[14:15]
	v_lshl_add_u64 v[14:15], s[6:7], 0, v[14:15]
	v_lshl_add_u64 v[14:15], v[14:15], 0, v[8:9]
	v_add_u32_e32 v18, 0x200, v12
	v_mov_b32_e32 v12, v18
	s_addc_u32 s11, s11, 0
	s_add_u32 s16, s16, 0x800
	s_addc_u32 s17, s17, 0
	s_add_u32 s14, s14, 0x800
	s_addc_u32 s15, s15, 0
	v_add_u32_e32 v1, 0x2000, v1
	v_mov_b32_e32 v116, v14
	v_mov_b32_e32 v117, v15
	v_lshl_add_u64 v[14:15], s[8:9], 0, v[2:3]
	v_add_co_u32_e32 v22, vcc, 0x1e200000, v14
	v_lshl_add_u64 v[16:17], s[10:11], 0, v[2:3]
	s_nop 0
	v_addc_co_u32_e32 v23, vcc, 0, v15, vcc
	v_add_co_u32_e32 v24, vcc, 0x1e205000, v14
	v_lshl_add_u64 v[18:19], s[16:17], 0, v[2:3]
	s_nop 0
	v_addc_co_u32_e32 v25, vcc, 0, v15, vcc
	v_add_co_u32_e32 v26, vcc, 0x1ea00000, v16
	global_load_dword v120, v[22:23], off
	global_load_dword v121, v[24:25], off offset:2048
	v_addc_co_u32_e32 v27, vcc, 0, v17, vcc
	v_add_co_u32_e32 v22, vcc, 0x1ea05000, v16
	v_lshl_add_u64 v[20:21], s[14:15], 0, v[2:3]
	s_nop 0
	v_addc_co_u32_e32 v23, vcc, 0, v17, vcc
	v_add_co_u32_e32 v24, vcc, 0x10000, v18
	global_load_dword v122, v[26:27], off
	global_load_dword v123, v[22:23], off offset:2048
	v_addc_co_u32_e32 v25, vcc, 0, v19, vcc
	v_add_co_u32_e32 v22, vcc, 0x16000, v18
	global_load_dword v124, v[24:25], off offset:2048
	s_nop 0
	v_addc_co_u32_e32 v23, vcc, 0, v19, vcc
	v_add_co_u32_e32 v24, vcc, 0x1b000, v18
	v_ashrrev_i32_e32 v8, 6, v12
	s_nop 0
	v_addc_co_u32_e32 v25, vcc, 0, v19, vcc
	v_add_co_u32_e32 v26, vcc, 0x5000, v20
	global_load_dword v125, v[22:23], off
	global_load_dword v126, v[24:25], off offset:2048
	v_addc_co_u32_e32 v27, vcc, 0, v21, vcc
	v_add_co_u32_e32 v22, vcc, 0x1e202000, v14
	global_load_dword v127, v[26:27], off offset:2048
	s_nop 0
	v_addc_co_u32_e32 v23, vcc, 0, v15, vcc
	v_add_co_u32_e32 v14, vcc, 0x1e208000, v14
	s_add_u32 s8, s8, 0x800
	s_nop 0
	v_addc_co_u32_e32 v15, vcc, 0, v15, vcc
	v_add_co_u32_e32 v24, vcc, 0x1ea02000, v16
	global_load_dword v128, v[22:23], off offset:3072
	global_load_dword v129, v[14:15], off offset:1024
	v_addc_co_u32_e32 v25, vcc, 0, v17, vcc
	v_add_co_u32_e32 v14, vcc, 0x1ea08000, v16
	global_load_dword v130, v[24:25], off offset:3072
	s_nop 0
	v_addc_co_u32_e32 v15, vcc, 0, v17, vcc
	v_add_co_u32_e32 v16, vcc, 0x13000, v18
	s_addc_u32 s9, s9, 0
	s_nop 0
	v_addc_co_u32_e32 v17, vcc, 0, v19, vcc
	v_add_co_u32_e32 v22, vcc, 0x18000, v18
	global_load_dword v131, v[16:17], off offset:1024
	s_nop 0
	v_addc_co_u32_e32 v23, vcc, 0, v19, vcc
	v_add_co_u32_e32 v16, vcc, 0x1e000, v18
	s_add_u32 s10, s10, 0x800
	s_nop 0
	v_addc_co_u32_e32 v17, vcc, 0, v19, vcc
	v_add_co_u32_e32 v18, vcc, 0x8000, v20
	global_load_dword v132, v[22:23], off offset:3072
	global_load_dword v133, v[16:17], off offset:1024
	v_addc_co_u32_e32 v19, vcc, 0, v21, vcc
	global_load_dword v134, v[18:19], off offset:1024
	global_load_dword v135, v[14:15], off offset:1024
	v_and_or_b32 v15, v1, s19, v10
	v_add_u32_e32 v14, s23, v8
	v_lshlrev_b32_e32 v8, 1, v15
	v_ashrrev_i32_e32 v15, 31, v14
	v_lshlrev_b64 v[14:15], 15, v[14:15]
	v_lshl_add_u64 v[14:15], s[6:7], 0, v[14:15]
	v_lshl_add_u64 v[14:15], v[14:15], 0, v[8:9]
	v_add_u32_e32 v18, 0x200, v12
	v_mov_b32_e32 v12, v18
	s_addc_u32 s11, s11, 0
	s_add_u32 s16, s16, 0x800
	s_addc_u32 s17, s17, 0
	s_add_u32 s14, s14, 0x800
	s_addc_u32 s15, s15, 0
	v_add_u32_e32 v1, 0x2000, v1
	v_mov_b32_e32 v136, v14
	v_mov_b32_e32 v137, v15
	s_nop 0
	v_readfirstlane_b32 s12, v12
	s_cmpk_gt_i32 s12, 0xaff
	s_cbranch_scc1 .Lfx1_issued
	v_lshl_add_u64 v[14:15], s[8:9], 0, v[2:3]
	v_add_co_u32_e32 v22, vcc, 0x1e200000, v14
	v_lshl_add_u64 v[16:17], s[10:11], 0, v[2:3]
	s_nop 0
	v_addc_co_u32_e32 v23, vcc, 0, v15, vcc
	v_add_co_u32_e32 v24, vcc, 0x1e205000, v14
	v_lshl_add_u64 v[18:19], s[16:17], 0, v[2:3]
	s_nop 0
	v_addc_co_u32_e32 v25, vcc, 0, v15, vcc
	v_add_co_u32_e32 v26, vcc, 0x1ea00000, v16
	global_load_dword v140, v[22:23], off
	global_load_dword v141, v[24:25], off offset:2048
	v_addc_co_u32_e32 v27, vcc, 0, v17, vcc
	v_add_co_u32_e32 v22, vcc, 0x1ea05000, v16
	v_lshl_add_u64 v[20:21], s[14:15], 0, v[2:3]
	s_nop 0
	v_addc_co_u32_e32 v23, vcc, 0, v17, vcc
	v_add_co_u32_e32 v24, vcc, 0x10000, v18
	global_load_dword v142, v[26:27], off
	global_load_dword v143, v[22:23], off offset:2048
	v_addc_co_u32_e32 v25, vcc, 0, v19, vcc
	v_add_co_u32_e32 v22, vcc, 0x16000, v18
	global_load_dword v144, v[24:25], off offset:2048
	s_nop 0
	v_addc_co_u32_e32 v23, vcc, 0, v19, vcc
	v_add_co_u32_e32 v24, vcc, 0x1b000, v18
	v_ashrrev_i32_e32 v8, 6, v12
	s_nop 0
	v_addc_co_u32_e32 v25, vcc, 0, v19, vcc
	v_add_co_u32_e32 v26, vcc, 0x5000, v20
	global_load_dword v145, v[22:23], off
	global_load_dword v146, v[24:25], off offset:2048
	v_addc_co_u32_e32 v27, vcc, 0, v21, vcc
	v_add_co_u32_e32 v22, vcc, 0x1e202000, v14
	global_load_dword v147, v[26:27], off offset:2048
	s_nop 0
	v_addc_co_u32_e32 v23, vcc, 0, v15, vcc
	v_add_co_u32_e32 v14, vcc, 0x1e208000, v14
	s_add_u32 s8, s8, 0x800
	s_nop 0
	v_addc_co_u32_e32 v15, vcc, 0, v15, vcc
	v_add_co_u32_e32 v24, vcc, 0x1ea02000, v16
	global_load_dword v148, v[22:23], off offset:3072
	global_load_dword v149, v[14:15], off offset:1024
	v_addc_co_u32_e32 v25, vcc, 0, v17, vcc
	v_add_co_u32_e32 v14, vcc, 0x1ea08000, v16
	global_load_dword v150, v[24:25], off offset:3072
	s_nop 0
	v_addc_co_u32_e32 v15, vcc, 0, v17, vcc
	v_add_co_u32_e32 v16, vcc, 0x13000, v18
	s_addc_u32 s9, s9, 0
	s_nop 0
	v_addc_co_u32_e32 v17, vcc, 0, v19, vcc
	v_add_co_u32_e32 v22, vcc, 0x18000, v18
	global_load_dword v151, v[16:17], off offset:1024
	s_nop 0
	v_addc_co_u32_e32 v23, vcc, 0, v19, vcc
	v_add_co_u32_e32 v16, vcc, 0x1e000, v18
	s_add_u32 s10, s10, 0x800
	s_nop 0
	v_addc_co_u32_e32 v17, vcc, 0, v19, vcc
	v_add_co_u32_e32 v18, vcc, 0x8000, v20
	global_load_dword v152, v[22:23], off offset:3072
	global_load_dword v153, v[16:17], off offset:1024
	v_addc_co_u32_e32 v19, vcc, 0, v21, vcc
	global_load_dword v154, v[18:19], off offset:1024
	global_load_dword v155, v[14:15], off offset:1024
	v_and_or_b32 v15, v1, s19, v10
	v_add_u32_e32 v14, s23, v8
	v_lshlrev_b32_e32 v8, 1, v15
	v_ashrrev_i32_e32 v15, 31, v14
	v_lshlrev_b64 v[14:15], 15, v[14:15]
	v_lshl_add_u64 v[14:15], s[6:7], 0, v[14:15]
	v_lshl_add_u64 v[14:15], v[14:15], 0, v[8:9]
	v_add_u32_e32 v18, 0x200, v12
	v_mov_b32_e32 v12, v18
	s_addc_u32 s11, s11, 0
	s_add_u32 s16, s16, 0x800
	s_addc_u32 s17, s17, 0
	s_add_u32 s14, s14, 0x800
	s_addc_u32 s15, s15, 0
	v_add_u32_e32 v1, 0x2000, v1
	v_mov_b32_e32 v156, v14
	v_mov_b32_e32 v157, v15
; __device__ __forceinline__ unsigned f2bf(float f) { unsigned u = __builtin_bit_cast(unsigned, f); return (u + 0x7fffu + ((u >> 16) & 1u)) >> 16; }
; __device__ __forceinline__ void ffn_fixup(int pm, const float* __restrict__ UH, const float* __restrict__ UT, const float* __restrict__ cw, const float* __restrict__ cb, bf16_t* __restrict__ ACT, int tid) {
;     ...
;             const float r0 = bb + w2 * h0 + w1 * q1 + w0 * q2, r1 = bb + w2 * h1 + w1 * h0 + w0 * q1;
;             if (hg == 0) { cva[0] = r0; cva[1] = r1; } else { cvg[0] = r0; cvg[1] = r1; }
;         }
; #pragma unroll
;         for (int r = 0; r < 2; ++r) { const float a = cva[r]; const float y = a * __builtin_amdgcn_rcpf(1.0f + __builtin_amdgcn_exp2f(-a * LOG2E)) * cvg[r];
;             ACT[pg8::aimg_off(pm * 256 + r, f, FF / 64)] = (bf16_t)f2bf(y); }
; __global__ void __launch_bounds__(512, 2) hybrid_fwd(Args args) {
;     ...
;           asm volatile("s_waitcnt vmcnt(0)" ::: "memory"); __syncthreads(); }
;         EpiRes<true> E{XB, out, SSQ};
;         pg8::gemm_phase<EpiRes<true>, true>(lds, g, S, E);
.Lfx1_issued:
	s_waitcnt vmcnt(0)
	v_fma_f32 v8, v40, v46, v47
	v_fmac_f32_e32 v47, v41, v46
	v_fmac_f32_e32 v8, v43, v45
	v_fmac_f32_e32 v47, v40, v45
	v_fmac_f32_e32 v8, v42, v44
	v_fmac_f32_e32 v47, v43, v44
	v_mul_f32_e32 v40, 0xbfb8aa3b, v8
	v_mul_f32_e32 v18, 0xbfb8aa3b, v47
	v_exp_f32_e32 v40, v40
	v_exp_f32_e32 v18, v18
	v_add_f32_e32 v40, 1.0, v40
	v_add_f32_e32 v18, 1.0, v18
	v_rcp_f32_e32 v40, v40
	v_rcp_f32_e32 v18, v18
	v_mul_f32_e32 v8, v8, v40
	v_mul_f32_e32 v40, v47, v18
	v_fma_f32 v19, v48, v53, v54
	v_fmac_f32_e32 v54, v49, v53
	v_fmac_f32_e32 v19, v55, v52
	v_fmac_f32_e32 v54, v48, v52
	v_fmac_f32_e32 v19, v50, v51
	v_fmac_f32_e32 v54, v55, v51
	v_mul_f32_e32 v8, v8, v19
	v_mul_f32_e32 v40, v40, v54
	v_bfe_u32 v54, v8, 16, 1
	v_bfe_u32 v55, v40, 16, 1
	v_add3_u32 v8, v8, v54, s20
	v_add3_u32 v40, v40, v55, s20
	global_store_short_d16_hi v[56:57], v8, off
	global_store_short_d16_hi v[56:57], v40, off offset:64
	v_fma_f32 v8, v60, v66, v67
	v_fmac_f32_e32 v67, v61, v66
	v_fmac_f32_e32 v8, v63, v65
	v_fmac_f32_e32 v67, v60, v65
	v_fmac_f32_e32 v8, v62, v64
	v_fmac_f32_e32 v67, v63, v64
	v_mul_f32_e32 v60, 0xbfb8aa3b, v8
	v_mul_f32_e32 v18, 0xbfb8aa3b, v67
	v_exp_f32_e32 v60, v60
	v_exp_f32_e32 v18, v18
	v_add_f32_e32 v60, 1.0, v60
	v_add_f32_e32 v18, 1.0, v18
	v_rcp_f32_e32 v60, v60
	v_rcp_f32_e32 v18, v18
	v_mul_f32_e32 v8, v8, v60
	v_mul_f32_e32 v60, v67, v18
	v_fma_f32 v19, v68, v73, v74
	v_fmac_f32_e32 v74, v69, v73
	v_fmac_f32_e32 v19, v75, v72
	v_fmac_f32_e32 v74, v68, v72
	v_fmac_f32_e32 v19, v70, v71
	v_fmac_f32_e32 v74, v75, v71
	v_mul_f32_e32 v8, v8, v19
	v_mul_f32_e32 v60, v60, v74
	v_bfe_u32 v74, v8, 16, 1
	v_bfe_u32 v75, v60, 16, 1
	v_add3_u32 v8, v8, v74, s20
	v_add3_u32 v60, v60, v75, s20
	global_store_short_d16_hi v[76:77], v8, off
	global_store_short_d16_hi v[76:77], v60, off offset:64
	v_fma_f32 v8, v80, v86, v87
	v_fmac_f32_e32 v87, v81, v86
	v_fmac_f32_e32 v8, v83, v85
	v_fmac_f32_e32 v87, v80, v85
	v_fmac_f32_e32 v8, v82, v84
	v_fmac_f32_e32 v87, v83, v84
	v_mul_f32_e32 v80, 0xbfb8aa3b, v8
	v_mul_f32_e32 v18, 0xbfb8aa3b, v87
	v_exp_f32_e32 v80, v80
	v_exp_f32_e32 v18, v18
	v_add_f32_e32 v80, 1.0, v80
	v_add_f32_e32 v18, 1.0, v18
	v_rcp_f32_e32 v80, v80
	v_rcp_f32_e32 v18, v18
	v_mul_f32_e32 v8, v8, v80
	v_mul_f32_e32 v80, v87, v18
	v_fma_f32 v19, v88, v93, v94
	v_fmac_f32_e32 v94, v89, v93
	v_fmac_f32_e32 v19, v95, v92
	v_fmac_f32_e32 v94, v88, v92
	v_fmac_f32_e32 v19, v90, v91
	v_fmac_f32_e32 v94, v95, v91
	v_mul_f32_e32 v8, v8, v19
	v_mul_f32_e32 v80, v80, v94
	v_bfe_u32 v94, v8, 16, 1
	v_bfe_u32 v95, v80, 16, 1
	v_add3_u32 v8, v8, v94, s20
	v_add3_u32 v80, v80, v95, s20
	global_store_short_d16_hi v[96:97], v8, off
	global_store_short_d16_hi v[96:97], v80, off offset:64
	v_fma_f32 v8, v100, v106, v107
	v_fmac_f32_e32 v107, v101, v106
	v_fmac_f32_e32 v8, v103, v105
	v_fmac_f32_e32 v107, v100, v105
	v_fmac_f32_e32 v8, v102, v104
	v_fmac_f32_e32 v107, v103, v104
	v_mul_f32_e32 v100, 0xbfb8aa3b, v8
	v_mul_f32_e32 v18, 0xbfb8aa3b, v107
	v_exp_f32_e32 v100, v100
	v_exp_f32_e32 v18, v18
	v_add_f32_e32 v100, 1.0, v100
	v_add_f32_e32 v18, 1.0, v18
	v_rcp_f32_e32 v100, v100
	v_rcp_f32_e32 v18, v18
	v_mul_f32_e32 v8, v8, v100
	v_mul_f32_e32 v100, v107, v18
	v_fma_f32 v19, v108, v113, v114
	v_fmac_f32_e32 v114, v109, v113
	v_fmac_f32_e32 v19, v115, v112
	v_fmac_f32_e32 v114, v108, v112
	v_fmac_f32_e32 v19, v110, v111
	v_fmac_f32_e32 v114, v115, v111
	v_mul_f32_e32 v8, v8, v19
	v_mul_f32_e32 v100, v100, v114
	v_bfe_u32 v114, v8, 16, 1
	v_bfe_u32 v115, v100, 16, 1
	v_add3_u32 v8, v8, v114, s20
	v_add3_u32 v100, v100, v115, s20
	global_store_short_d16_hi v[116:117], v8, off
	global_store_short_d16_hi v[116:117], v100, off offset:64
	v_fma_f32 v8, v120, v126, v127
	v_fmac_f32_e32 v127, v121, v126
	v_fmac_f32_e32 v8, v123, v125
	v_fmac_f32_e32 v127, v120, v125
	v_fmac_f32_e32 v8, v122, v124
	v_fmac_f32_e32 v127, v123, v124
	v_mul_f32_e32 v120, 0xbfb8aa3b, v8
	v_mul_f32_e32 v18, 0xbfb8aa3b, v127
	v_exp_f32_e32 v120, v120
	v_exp_f32_e32 v18, v18
	v_add_f32_e32 v120, 1.0, v120
	v_add_f32_e32 v18, 1.0, v18
	v_rcp_f32_e32 v120, v120
	v_rcp_f32_e32 v18, v18
	v_mul_f32_e32 v8, v8, v120
	v_mul_f32_e32 v120, v127, v18
	v_fma_f32 v19, v128, v133, v134
	v_fmac_f32_e32 v134, v129, v133
	v_fmac_f32_e32 v19, v135, v132
	v_fmac_f32_e32 v134, v128, v132
	v_fmac_f32_e32 v19, v130, v131
	v_fmac_f32_e32 v134, v135, v131
	v_mul_f32_e32 v8, v8, v19
	v_mul_f32_e32 v120, v120, v134
	v_bfe_u32 v134, v8, 16, 1
	v_bfe_u32 v135, v120, 16, 1
	v_add3_u32 v8, v8, v134, s20
	v_add3_u32 v120, v120, v135, s20
	global_store_short_d16_hi v[136:137], v8, off
	global_store_short_d16_hi v[136:137], v120, off offset:64
	s_cmpk_gt_i32 s12, 0xaff
	s_cbranch_scc1 .Lfx1_done
	v_fma_f32 v8, v140, v146, v147
	v_fmac_f32_e32 v147, v141, v146
	v_fmac_f32_e32 v8, v143, v145
	v_fmac_f32_e32 v147, v140, v145
	v_fmac_f32_e32 v8, v142, v144
	v_fmac_f32_e32 v147, v143, v144
	v_mul_f32_e32 v140, 0xbfb8aa3b, v8
	v_mul_f32_e32 v18, 0xbfb8aa3b, v147
	v_exp_f32_e32 v140, v140
	v_exp_f32_e32 v18, v18
	v_add_f32_e32 v140, 1.0, v140
	v_add_f32_e32 v18, 1.0, v18
	v_rcp_f32_e32 v140, v140
	v_rcp_f32_e32 v18, v18
	v_mul_f32_e32 v8, v8, v140
	v_mul_f32_e32 v140, v147, v18
	v_fma_f32 v19, v148, v153, v154
	v_fmac_f32_e32 v154, v149, v153
	v_fmac_f32_e32 v19, v155, v152
	v_fmac_f32_e32 v154, v148, v152
	v_fmac_f32_e32 v19, v150, v151
	v_fmac_f32_e32 v154, v155, v151
	v_mul_f32_e32 v8, v8, v19
	v_mul_f32_e32 v140, v140, v154
	v_bfe_u32 v154, v8, 16, 1
	v_bfe_u32 v155, v140, 16, 1
	v_add3_u32 v8, v8, v154, s20
	v_add3_u32 v140, v140, v155, s20
	global_store_short_d16_hi v[156:157], v8, off
	global_store_short_d16_hi v[156:157], v140, off offset:64
.Lfx1_done:
	s_branch .LBB0_1374
.LBB0_1386:
	s_waitcnt vmcnt(0)
	v_mov_b32_e32 v0, v220
	s_waitcnt vmcnt(0)
	s_barrier
	s_cmpk_gt_i32 s2, 0x1ff
	v_readfirstlane_b32 s4, v0
	s_cbranch_scc1 .LBB0_1414
	s_ashr_i32 s0, s2, 31
	s_lshr_b32 s0, s0, 29
	s_add_i32 s9, s2, s0
	s_and_b32 s0, s9, -8
	s_sub_i32 s8, s2, s0
	s_cmp_gt_i32 s8, -1
	s_cbranch_scc0 .LBB0_1389
	s_lshl_b32 s5, s8, 6
	s_ashr_i32 s0, s9, 3
	s_cbranch_execz .LBB0_1390
	s_branch .LBB0_1391
